# static s_setprio 1 for waves 4-7 during NSA attention units (reset at unit end), on top of epilogue load hoists and flag-read fix
# speedup vs baseline: 1.0211x; 1.0091x over previous
; __global__ void __launch_bounds__(NTHR, 2) hybrid_fwd(P p) {
;     ...
;             for (;;) {
;                 if (tid == 0) *qslot = atomicAdd(qctr, 1u);
;                 __syncthreads();
;                 const int v = (int)*qslot;
;                 __syncthreads();
;                 if (v >= 1024) break;
.LBB0_518:
	s_setprio 0
	s_mov_b64 s[2:3], 0

; #define LAS __attribute__((address_space(3)))
; DI int tid_of(int wv) { int ln; asm volatile("v_mbcnt_lo_u32_b32 %0, -1, 0\n\tv_mbcnt_hi_u32_b32 %0, -1, %0" : "=v"(ln)); return wv * 64 + ln; }
; DI void load_q(bf16x8 (&q)[8], const bf16* qrow, int h, const float* gain, int lane) {
;     float ss = 0.f;
; #pragma unroll
;     for (int s = 0; s < 8; ++s) { const u32x4 raw = *(const u32x4*)(qrow + 16 * s + 8 * h);
; #pragma unroll
;         for (int j = 0; j < 4; ++j) { const float a = __builtin_bit_cast(float, raw[j] << 16), b = __builtin_bit_cast(float, raw[j] & 0xffff0000u); ss += a * a + b * b; } }
; DI void nsa_unit(const P& p, ldsp lds, int u, int l, int wv) {
;     const int tid = tid_of(wv), lane = tid & 63, w = tid >> 6, r32 = lane & 31, h = lane >> 5;
;     const int qb = 127 - (u >> 2), bg = u & 3, b = bg >> 1, g = bg & 1;
;     const bf16* heads = (const bf16*)(p.ws + WS_HEADS); const bf16* VT = (const bf16*)(p.ws + WS_VT);
;     const int ql = r32 >> 2, r = r32 & 3, qi = w * 8 + ql, t = qb * 64 + qi, hn = g * 4 + r;
; #pragma unroll
;     for (int k = 0; k < 8; ++k) *(LAS f32x4*)(lds + A_IMPG + (k * 512 + tid) * 16) = (f32x4){0.f, 0.f, 0.f, 0.f};
;     bf16x8 q[8]; load_q(q, heads + ((size_t)(16 + hn) * M + b * T + t) * HD, h, p.nqn + l * HD, lane);
.LBB0_588:
	s_and_b64 vcc, exec, s[2:3]
	s_cbranch_vccz .LBB0_518
	s_cmpk_gt_i32 s30, 0xff
	s_cselect_b64 s[6:7], -1, 0
	s_lshl_b32 s2, s30, 1
	s_bfe_u32 s0, s2, 0x70002
	v_writelane_b32 v255, s0, 19
	s_xor_b32 s0, s0, 0x7f
	s_lshl_b32 s1, s0, 6
	s_cmpk_lt_i32 s30, 0x100
	s_cselect_b64 s[8:9], -1, 0
	v_readlane_b32 s3, v252, 5
	s_nop 0
	s_cmp_ge_u32 s3, 0x100
	s_cbranch_scc0 .Lnsa_prio_skip
	s_setprio 1
.Lnsa_prio_skip:
	v_mbcnt_lo_u32_b32 v200, -1, 0
	v_mbcnt_hi_u32_b32 v200, -1, v200
	s_and_b64 vcc, s[8:9], exec
	v_and_b32_e32 v159, 3, v200
	v_add_u32_e32 v168, s3, v200
	v_ashrrev_i32_e32 v166, 6, v168
	s_cselect_b32 s3, 4, 0
	v_bfe_u32 v198, v200, 2, 3
	v_lshlrev_b32_e32 v199, 3, v166
	v_or_b32_e32 v196, s3, v159
	s_lshl_b32 s3, s30, 13
	v_or_b32_e32 v147, v199, v198
	s_and_b32 s3, s3, 0x2000
	v_add_u32_e32 v148, s1, v147
	v_lshl_or_b32 v0, v196, 14, s3
	v_or_b32_e32 v0, 0x40000, v0
	v_ashrrev_i32_e32 v149, 31, v148
	v_lshl_add_u64 v[2:3], v[0:1], 0, v[148:149]
	v_readlane_b32 s4, v253, 10
	v_bfe_u32 v201, v200, 5, 1
	v_lshlrev_b64 v[2:3], 8, v[2:3]
	v_readlane_b32 s5, v253, 11
	v_lshlrev_b32_e32 v156, 4, v201
	v_mov_b32_e32 v157, v1
	v_lshl_add_u64 v[2:3], s[4:5], 0, v[2:3]
	v_lshl_add_u64 v[110:111], v[2:3], 0, v[156:157]
	global_load_dwordx4 v[6:9], v[110:111], off
	global_load_dwordx4 v[10:13], v[110:111], off offset:32
	global_load_dwordx4 v[14:17], v[110:111], off offset:64
	global_load_dwordx4 v[2:5], v[110:111], off offset:96
	s_mov_b32 s18, s17
	s_mov_b32 s19, s17
	v_lshlrev_b32_e32 v157, 4, v168
	s_mov_b32 s16, s17
	v_mov_b64_e32 v[20:21], s[18:19]
	v_add_u32_e32 v0, 0, v157
	v_mov_b64_e32 v[18:19], s[16:17]
	v_add_u32_e32 v0, 0x11a00, v0
	ds_write_b128 v0, v[18:21]
	ds_write_b128 v0, v[18:21] offset:8192
	ds_write_b128 v0, v[18:21] offset:16384
	ds_write_b128 v0, v[18:21] offset:24576
	ds_write_b128 v0, v[18:21] offset:32768
	ds_write_b128 v0, v[18:21] offset:40960
	ds_write_b128 v0, v[18:21] offset:49152
	ds_write_b128 v0, v[18:21] offset:57344
	global_load_dwordx4 v[34:37], v[110:111], off offset:128
	global_load_dwordx4 v[38:41], v[110:111], off offset:160
	v_writelane_b32 v255, s3, 20
	global_load_dwordx4 v[106:109], v[110:111], off offset:192
	global_load_dwordx4 v[112:115], v[110:111], off offset:224
	v_readlane_b32 s4, v255, 13
	v_readlane_b32 s5, v255, 14
	v_and_b32_e32 v167, 63, v200
	v_lshlrev_b32_e32 v169, 2, v167
	v_xor_b32_e32 v197, 0x80, v169
	v_mov_b32_e32 v190, 0
	v_xor_b32_e32 v170, 4, v169
	v_xor_b32_e32 v171, 8, v169
	v_mov_b32_e32 v154, 0
	s_waitcnt vmcnt(0)
	v_lshlrev_b32_e32 v0, 16, v6
	v_and_b32_e32 v6, 0xffff0000, v6
	v_lshlrev_b32_e32 v18, 16, v7
	v_and_b32_e32 v7, 0xffff0000, v7
	v_lshlrev_b32_e32 v19, 16, v8
	v_and_b32_e32 v8, 0xffff0000, v8
	v_mul_f32_e32 v6, v6, v6
	v_mul_f32_e32 v7, v7, v7
	v_lshlrev_b32_e32 v20, 16, v9
	v_and_b32_e32 v9, 0xffff0000, v9
	v_mul_f32_e32 v8, v8, v8
	v_fmac_f32_e32 v6, v0, v0
	v_fmac_f32_e32 v7, v18, v18
	v_lshlrev_b32_e32 v21, 16, v10
	v_and_b32_e32 v10, 0xffff0000, v10
	v_mul_f32_e32 v9, v9, v9
	v_fmac_f32_e32 v8, v19, v19
	v_add_f32_e32 v0, v6, v7
	v_lshlrev_b32_e32 v22, 16, v11
	v_and_b32_e32 v11, 0xffff0000, v11
	v_mul_f32_e32 v10, v10, v10
	v_fmac_f32_e32 v9, v20, v20
	v_add_f32_e32 v0, v8, v0
	v_lshlrev_b32_e32 v23, 16, v12
	v_and_b32_e32 v12, 0xffff0000, v12
	v_mul_f32_e32 v11, v11, v11
	v_fmac_f32_e32 v10, v21, v21
	v_add_f32_e32 v0, v9, v0
	v_lshlrev_b32_e32 v24, 16, v13
	v_and_b32_e32 v13, 0xffff0000, v13
	v_mul_f32_e32 v12, v12, v12
	v_fmac_f32_e32 v11, v22, v22
	v_add_f32_e32 v0, v10, v0
	v_lshlrev_b32_e32 v25, 16, v14
	v_and_b32_e32 v14, 0xffff0000, v14
	v_mul_f32_e32 v13, v13, v13
	v_fmac_f32_e32 v12, v23, v23
	v_add_f32_e32 v0, v11, v0
	v_lshlrev_b32_e32 v26, 16, v15
	v_and_b32_e32 v15, 0xffff0000, v15
	v_mul_f32_e32 v14, v14, v14
	v_fmac_f32_e32 v13, v24, v24
	v_add_f32_e32 v0, v12, v0
	v_lshlrev_b32_e32 v27, 16, v16
	v_and_b32_e32 v16, 0xffff0000, v16
	v_mul_f32_e32 v15, v15, v15
	v_fmac_f32_e32 v14, v25, v25
	v_add_f32_e32 v0, v13, v0
	v_lshlrev_b32_e32 v28, 16, v17
	v_and_b32_e32 v17, 0xffff0000, v17
	v_mul_f32_e32 v16, v16, v16
	v_fmac_f32_e32 v15, v26, v26
	v_add_f32_e32 v0, v14, v0
	v_fmac_f32_e32 v16, v27, v27
	v_add_f32_e32 v0, v15, v0
	v_mul_f32_e32 v6, v17, v17
	v_add_f32_e32 v0, v16, v0
	v_fmac_f32_e32 v6, v28, v28
	v_add_f32_e32 v0, v6, v0
	v_lshlrev_b32_e32 v6, 16, v2
	v_and_b32_e32 v2, 0xffff0000, v2
	v_mul_f32_e32 v2, v2, v2
	v_fmac_f32_e32 v2, v6, v6
	v_add_f32_e32 v0, v2, v0
	v_lshlrev_b32_e32 v2, 16, v3
	v_and_b32_e32 v3, 0xffff0000, v3
	v_mul_f32_e32 v3, v3, v3
	v_fmac_f32_e32 v3, v2, v2
	v_add_f32_e32 v0, v3, v0
	v_and_b32_e32 v3, 0xffff0000, v4
	v_lshlrev_b32_e32 v2, 16, v4
	v_mul_f32_e32 v3, v3, v3
	v_fmac_f32_e32 v3, v2, v2
	v_add_f32_e32 v0, v3, v0
	v_and_b32_e32 v3, 0xffff0000, v5
	v_lshlrev_b32_e32 v2, 16, v5
	v_mul_f32_e32 v3, v3, v3
	v_fmac_f32_e32 v3, v2, v2
	v_and_b32_e32 v10, 32, v200
	v_add_f32_e32 v0, v3, v0
	global_load_dwordx4 v[94:97], v10, s[4:5] offset:16
	global_load_dwordx4 v[102:105], v10, s[4:5]
	global_load_dwordx4 v[98:101], v[110:111], off
	global_load_dwordx4 v[86:89], v[110:111], off offset:32
	global_load_dwordx4 v[82:85], v10, s[4:5] offset:80
	global_load_dwordx4 v[90:93], v10, s[4:5] offset:64
	global_load_dwordx4 v[70:73], v10, s[4:5] offset:144
	global_load_dwordx4 v[78:81], v10, s[4:5] offset:128
	global_load_dwordx4 v[74:77], v[110:111], off offset:64
	global_load_dwordx4 v[62:65], v[110:111], off offset:96
; DI float shx(float v, int m, int lane) { return __builtin_bit_cast(float, __builtin_amdgcn_ds_bpermute((lane ^ m) << 2, __builtin_bit_cast(int, v))); }
; DI void load_q(bf16x8 (&q)[8], const bf16* qrow, int h, const float* gain, int lane) {
;     ...
;     for (int s = 0; s < 8; ++s) { const u32x4 raw = *(const u32x4*)(qrow + 16 * s + 8 * h);
; #pragma unroll
;         for (int j = 0; j < 4; ++j) { const float a = __builtin_bit_cast(float, raw[j] << 16), b = __builtin_bit_cast(float, raw[j] & 0xffff0000u); ss += a * a + b * b; } }
;     ss += shx(ss, 32, lane);
;     const float rs = rsqrtf(ss * (1.0f / HD) + EPS) * C2;
;     asm volatile("" ::: "memory");
; #pragma unroll
;     for (int s = 0; s < 8; ++s) {
;         const u32x4 raw = *(const u32x4*)(qrow + 16 * s + 8 * h);
;         const f32x4 g0 = *(const f32x4*)(gain + 16 * s + 8 * h), g1 = *(const f32x4*)(gain + 16 * s + 8 * h + 4);
; DI void nsa_unit(const P& p, ldsp lds, int u, int l, int wv) {
;     ...
;     if (g == 0) { const float* fq = p.nqn + l * HD; const float* fk = p.skn + l * HD; const float* fc = p.ckn + l * HD;
;       float gq = fmaxf(fabsf(fq[lane]), fabsf(fq[lane + 64])), gk = fmaxf(fmaxf(fabsf(fk[lane]), fabsf(fk[lane + 64])), fmaxf(fabsf(fc[lane]), fabsf(fc[lane + 64])));
; #pragma unroll
;       for (int o2 = 1; o2 < 64; o2 <<= 1) { gq = fmaxf(gq, shx(gq, o2, lane)); gk = fmaxf(gk, shx(gk, o2, lane)); }
;       c.bqk = 1.02f * C2 * 128.0f * gq * gk; }
	global_load_dwordx4 v[58:61], v10, s[4:5] offset:208
	global_load_dwordx4 v[66:69], v10, s[4:5] offset:192
	global_load_dwordx4 v[46:49], v10, s[4:5] offset:272
	global_load_dwordx4 v[54:57], v10, s[4:5] offset:256
	global_load_dwordx4 v[50:53], v[110:111], off offset:128
	global_load_dwordx4 v[30:33], v[110:111], off offset:160
	global_load_dwordx4 v[26:29], v10, s[4:5] offset:336
	global_load_dwordx4 v[42:45], v10, s[4:5] offset:320
	global_load_dwordx4 v[14:17], v10, s[4:5] offset:400
	global_load_dwordx4 v[22:25], v10, s[4:5] offset:384
	global_load_dwordx4 v[18:21], v[110:111], off offset:192
	global_load_dwordx4 v[6:9], v[110:111], off offset:224
	global_load_dwordx4 v[2:5], v10, s[4:5] offset:464
	s_nop 0
	global_load_dwordx4 v[10:13], v10, s[4:5] offset:448
	v_lshlrev_b32_e32 v110, 16, v34
	v_and_b32_e32 v34, 0xffff0000, v34
	v_mul_f32_e32 v34, v34, v34
	v_fmac_f32_e32 v34, v110, v110
	v_add_f32_e32 v0, v34, v0
	v_lshlrev_b32_e32 v34, 16, v35
	v_and_b32_e32 v35, 0xffff0000, v35
	v_mul_f32_e32 v35, v35, v35
	v_fmac_f32_e32 v35, v34, v34
	v_add_f32_e32 v0, v35, v0
	v_and_b32_e32 v35, 0xffff0000, v36
	v_lshlrev_b32_e32 v34, 16, v36
	v_mul_f32_e32 v35, v35, v35
	v_fmac_f32_e32 v35, v34, v34
	v_add_f32_e32 v0, v35, v0
	v_and_b32_e32 v35, 0xffff0000, v37
	v_lshlrev_b32_e32 v34, 16, v37
	v_mul_f32_e32 v35, v35, v35
	v_fmac_f32_e32 v35, v34, v34
	v_add_f32_e32 v0, v35, v0
	v_and_b32_e32 v35, 0xffff0000, v38
	v_lshlrev_b32_e32 v34, 16, v38
	v_mul_f32_e32 v35, v35, v35
	v_fmac_f32_e32 v35, v34, v34
	v_add_f32_e32 v0, v35, v0
	v_and_b32_e32 v35, 0xffff0000, v39
	v_lshlrev_b32_e32 v34, 16, v39
	v_mul_f32_e32 v35, v35, v35
	v_fmac_f32_e32 v35, v34, v34
	v_and_b32_e32 v37, 0xffff0000, v41
	v_and_b32_e32 v36, 0xffff0000, v40
	v_add_f32_e32 v0, v35, v0
	v_lshlrev_b32_e32 v35, 16, v41
	v_lshlrev_b32_e32 v34, 16, v40
	v_pk_mul_f32 v[36:37], v[36:37], v[36:37]
	s_nop 0
	v_pk_fma_f32 v[34:35], v[34:35], v[34:35], v[36:37]
	v_and_b32_e32 v37, 0xffff0000, v107
	v_add_f32_e32 v0, v34, v0
	v_and_b32_e32 v36, 0xffff0000, v106
	v_add_f32_e32 v0, v35, v0
	v_lshlrev_b32_e32 v35, 16, v107
	v_lshlrev_b32_e32 v34, 16, v106
	v_pk_mul_f32 v[36:37], v[36:37], v[36:37]
	s_nop 0
	v_pk_fma_f32 v[34:35], v[34:35], v[34:35], v[36:37]
	v_and_b32_e32 v37, 0xffff0000, v109
	v_add_f32_e32 v0, v34, v0
	v_and_b32_e32 v36, 0xffff0000, v108
	v_add_f32_e32 v0, v35, v0
	v_lshlrev_b32_e32 v35, 16, v109
	v_lshlrev_b32_e32 v34, 16, v108
	v_pk_mul_f32 v[36:37], v[36:37], v[36:37]
	s_nop 0
	v_pk_fma_f32 v[34:35], v[34:35], v[34:35], v[36:37]
	v_and_b32_e32 v37, 0xffff0000, v113
	v_add_f32_e32 v0, v34, v0
	v_and_b32_e32 v36, 0xffff0000, v112
	v_add_f32_e32 v0, v35, v0
	v_lshlrev_b32_e32 v35, 16, v113
	v_lshlrev_b32_e32 v34, 16, v112
	v_pk_mul_f32 v[36:37], v[36:37], v[36:37]
	s_nop 0
	v_pk_fma_f32 v[34:35], v[34:35], v[34:35], v[36:37]
	v_and_b32_e32 v37, 0xffff0000, v115
	v_add_f32_e32 v0, v34, v0
	v_and_b32_e32 v36, 0xffff0000, v114
	v_add_f32_e32 v0, v35, v0
	v_lshlrev_b32_e32 v35, 16, v115
	v_lshlrev_b32_e32 v34, 16, v114
	v_pk_mul_f32 v[36:37], v[36:37], v[36:37]
	s_nop 0
	v_pk_fma_f32 v[34:35], v[34:35], v[34:35], v[36:37]
	s_nop 0
	v_add_f32_e32 v0, v34, v0
	v_add_f32_e32 v0, v35, v0
	ds_bpermute_b32 v106, v197, v0
	s_cbranch_vccnz .LBB0_591
	v_readlane_b32 s4, v255, 13
	v_readlane_b32 s5, v255, 14
	s_nop 4
	global_load_dword v34, v169, s[4:5]
	global_load_dword v35, v169, s[4:5] offset:256
	v_readlane_b32 s4, v255, 15
	v_readlane_b32 s5, v255, 16
	s_waitcnt vmcnt(1)
	v_max_f32_e64 v34, |v34|, |v34|
	s_waitcnt vmcnt(0)
	v_max_f32_e64 v35, |v35|, |v35|
	v_max_f32_e32 v34, v34, v35
	global_load_dword v35, v169, s[4:5]
	global_load_dword v36, v169, s[4:5] offset:256
	v_readlane_b32 s4, v255, 17
	v_readlane_b32 s5, v255, 18
	s_nop 4
	global_load_dword v37, v169, s[4:5]
	global_load_dword v38, v169, s[4:5] offset:256
	s_waitcnt vmcnt(1)
	v_max_f32_e64 v37, |v37|, |v37|
	s_waitcnt vmcnt(0)
	v_max_f32_e64 v38, |v38|, |v38|
	v_max_f32_e32 v37, v37, v38
	v_max3_f32 v35, |v35|, |v36|, v37
	ds_bpermute_b32 v36, v170, v34
	s_waitcnt lgkmcnt(0)
	v_max_f32_e32 v36, v36, v36
	v_max_f32_e32 v34, v34, v36
	ds_bpermute_b32 v36, v170, v35
	s_waitcnt lgkmcnt(0)
	v_max_f32_e32 v36, v36, v36
	v_max_f32_e32 v35, v35, v36
	ds_bpermute_b32 v36, v171, v34
	s_waitcnt lgkmcnt(0)
	v_max_f32_e32 v36, v36, v36
	v_max_f32_e32 v34, v34, v36
	ds_bpermute_b32 v36, v171, v35
	s_waitcnt lgkmcnt(0)
	v_max_f32_e32 v36, v36, v36
	v_max_f32_e32 v35, v35, v36
	v_xor_b32_e32 v36, 16, v169
	ds_bpermute_b32 v37, v36, v34
	ds_bpermute_b32 v36, v36, v35
	s_waitcnt lgkmcnt(1)
	v_max_f32_e32 v37, v37, v37
	s_waitcnt lgkmcnt(0)
	v_max_f32_e32 v36, v36, v36
	v_max_f32_e32 v34, v34, v37
	v_max_f32_e32 v35, v35, v36
	v_xor_b32_e32 v36, 32, v169
	ds_bpermute_b32 v37, v36, v34
	ds_bpermute_b32 v36, v36, v35
	s_waitcnt lgkmcnt(1)
	v_max_f32_e32 v37, v37, v37
	s_waitcnt lgkmcnt(0)
	v_max_f32_e32 v36, v36, v36
	v_max_f32_e32 v34, v34, v37
	v_max_f32_e32 v35, v35, v36
	v_xor_b32_e32 v36, 64, v169
	ds_bpermute_b32 v37, v36, v34
	ds_bpermute_b32 v36, v36, v35
	s_waitcnt lgkmcnt(1)
	v_max_f32_e32 v37, v37, v37
	v_max_f32_e32 v34, v34, v37
	s_waitcnt lgkmcnt(0)
	v_max_f32_e32 v36, v36, v36
	v_max_f32_e32 v35, v35, v36
	ds_bpermute_b32 v36, v197, v34
	s_waitcnt lgkmcnt(0)
	v_max_f32_e32 v36, v36, v36
	v_max_f32_e32 v34, v34, v36
	ds_bpermute_b32 v36, v197, v35
	v_mul_f32_e32 v34, 0x4185307d, v34
	s_waitcnt lgkmcnt(0)
	v_max_f32_e32 v36, v36, v36
	v_max_f32_e32 v35, v35, v36
	v_mul_f32_e32 v154, v35, v34
